# hand-written softmax epilogue (S phase: grouped rows, packed f32, progressive stores) + hand-written relu2 epilogue (UP phase: row scales reused while the row panel is unchanged)
# speedup vs baseline: 1.0116x; 1.0116x over previous
.LBB0_517:
	s_mov_b32 s35, s34
	v_lshl_add_u32 v227, s34, 8, v166
	v_lshlrev_b32_e32 v227, 6, v227
	v_add_co_u32_e32 v162, vcc, v136, v227
	s_nop 1
	v_addc_co_u32_e32 v163, vcc, 0, v137, vcc
	v_add_co_u32_e32 v164, vcc, 0x2000, v162
	s_nop 1
	v_addc_co_u32_e32 v165, vcc, 0, v163, vcc
	global_load_dwordx4 v[146:149], v[162:163], off
	global_load_dwordx4 v[150:153], v[162:163], off offset:1024
	global_load_dwordx4 v[154:157], v[162:163], off offset:2048
	global_load_dwordx4 v[158:161], v[162:163], off offset:3072
	global_load_dwordx4 v[182:185], v[164:165], off
	global_load_dwordx4 v[186:189], v[164:165], off offset:1024
	global_load_dwordx4 v[190:193], v[164:165], off offset:2048
	global_load_dwordx4 v[194:197], v[164:165], off offset:3072
	v_xor_b32_e32 v198, 16, v173
	v_xor_b32_e32 v199, 32, v173
	v_lshlrev_b32_e32 v198, 2, v198
	v_lshlrev_b32_e32 v199, 2, v199
	v_max3_f32 v202, v124, v125, v126
	v_max3_f32 v203, v127, v120, v121
	v_max3_f32 v202, v202, v122, v123
	v_max3_f32 v203, v203, v116, v117
	v_max3_f32 v202, v202, v118, v119
	v_max3_f32 v203, v203, v112, v113
	v_max3_f32 v202, v202, v114, v115
	v_max_f32_e32 v202, v202, v203
	v_max3_f32 v204, v108, v109, v110
	v_max3_f32 v205, v111, v104, v105
	v_max3_f32 v204, v204, v106, v107
	v_max3_f32 v205, v205, v100, v101
	v_max3_f32 v204, v204, v102, v103
	v_max3_f32 v205, v205, v96, v97
	v_max3_f32 v204, v204, v98, v99
	v_max_f32_e32 v204, v204, v205
	v_max3_f32 v206, v92, v93, v94
	v_max3_f32 v207, v95, v88, v89
	v_max3_f32 v206, v206, v90, v91
	v_max3_f32 v207, v207, v84, v85
	v_max3_f32 v206, v206, v86, v87
	v_max3_f32 v207, v207, v80, v81
	v_max3_f32 v206, v206, v82, v83
	v_max_f32_e32 v206, v206, v207
	v_max3_f32 v208, v76, v77, v78
	v_max3_f32 v209, v79, v72, v73
	v_max3_f32 v208, v208, v74, v75
	v_max3_f32 v209, v209, v68, v69
	v_max3_f32 v208, v208, v70, v71
	v_max3_f32 v209, v209, v64, v65
	v_max3_f32 v208, v208, v66, v67
	v_max_f32_e32 v208, v208, v209
	v_max3_f32 v210, v60, v61, v62
	v_max3_f32 v211, v63, v56, v57
	v_max3_f32 v210, v210, v58, v59
	v_max3_f32 v211, v211, v52, v53
	v_max3_f32 v210, v210, v54, v55
	v_max3_f32 v211, v211, v48, v49
	v_max3_f32 v210, v210, v50, v51
	v_max_f32_e32 v210, v210, v211
	v_max3_f32 v212, v44, v45, v46
	v_max3_f32 v213, v47, v40, v41
	v_max3_f32 v212, v212, v42, v43
	v_max3_f32 v213, v213, v36, v37
	v_max3_f32 v212, v212, v38, v39
	v_max3_f32 v213, v213, v32, v33
	v_max3_f32 v212, v212, v34, v35
	v_max_f32_e32 v212, v212, v213
	v_max3_f32 v214, v28, v29, v30
	v_max3_f32 v215, v31, v24, v25
	v_max3_f32 v214, v214, v26, v27
	v_max3_f32 v215, v215, v20, v21
	v_max3_f32 v214, v214, v22, v23
	v_max3_f32 v215, v215, v16, v17
	v_max3_f32 v214, v214, v18, v19
	v_max_f32_e32 v214, v214, v215
	v_max3_f32 v216, v12, v13, v14
	v_max3_f32 v217, v15, v8, v9
	v_max3_f32 v216, v216, v10, v11
	v_max3_f32 v217, v217, v4, v5
	v_max3_f32 v216, v216, v6, v7
	v_max3_f32 v217, v217, v0, v1
	v_max3_f32 v216, v216, v2, v3
	v_max_f32_e32 v216, v216, v217
	ds_bpermute_b32 v249, v198, v202
	ds_bpermute_b32 v250, v198, v204
	ds_bpermute_b32 v251, v198, v206
	ds_bpermute_b32 v226, v198, v208
	ds_bpermute_b32 v162, v198, v210
	ds_bpermute_b32 v163, v198, v212
	ds_bpermute_b32 v164, v198, v214
	ds_bpermute_b32 v165, v198, v216
	s_waitcnt lgkmcnt(7)
	v_max_f32_e32 v202, v202, v249
	s_waitcnt lgkmcnt(6)
	v_max_f32_e32 v204, v204, v250
	s_waitcnt lgkmcnt(5)
	v_max_f32_e32 v206, v206, v251
	s_waitcnt lgkmcnt(4)
	v_max_f32_e32 v208, v208, v226
	s_waitcnt lgkmcnt(3)
	v_max_f32_e32 v210, v210, v162
	s_waitcnt lgkmcnt(2)
	v_max_f32_e32 v212, v212, v163
	s_waitcnt lgkmcnt(1)
	v_max_f32_e32 v214, v214, v164
	s_waitcnt lgkmcnt(0)
	v_max_f32_e32 v216, v216, v165
	ds_bpermute_b32 v249, v199, v202
	ds_bpermute_b32 v250, v199, v204
	ds_bpermute_b32 v251, v199, v206
	ds_bpermute_b32 v226, v199, v208
	ds_bpermute_b32 v162, v199, v210
	ds_bpermute_b32 v163, v199, v212
	ds_bpermute_b32 v164, v199, v214
	ds_bpermute_b32 v165, v199, v216
	s_waitcnt lgkmcnt(7)
	v_max_f32_e32 v202, v202, v249
	s_waitcnt lgkmcnt(6)
	v_max_f32_e32 v204, v204, v250
	s_waitcnt lgkmcnt(5)
	v_max_f32_e32 v206, v206, v251
	s_waitcnt lgkmcnt(4)
	v_max_f32_e32 v208, v208, v226
	s_waitcnt lgkmcnt(3)
	v_max_f32_e32 v210, v210, v162
	s_waitcnt lgkmcnt(2)
	v_max_f32_e32 v212, v212, v163
	s_waitcnt lgkmcnt(1)
	v_max_f32_e32 v214, v214, v164
	s_waitcnt lgkmcnt(0)
	v_max_f32_e32 v216, v216, v165
	v_lshl_add_u32 v229, s35, 8, v166
	v_lshlrev_b32_e32 v229, 11, v229
	v_lshl_or_b32 v228, s57, 9, v169
	v_add_u32_e32 v229, v229, v228
	v_add_u32_e32 v201, s53, v168
	s_waitcnt vmcnt(7)
	v_add_f32_e32 v146, v146, v147
	v_add_f32_e32 v148, v148, v149
	v_add_f32_e32 v218, v146, v148
	s_waitcnt vmcnt(6)
	v_add_f32_e32 v150, v150, v151
	v_add_f32_e32 v152, v152, v153
	v_add_f32_e32 v219, v150, v152
	s_waitcnt vmcnt(5)
	v_add_f32_e32 v154, v154, v155
	v_add_f32_e32 v156, v156, v157
	v_add_f32_e32 v220, v154, v156
	s_waitcnt vmcnt(4)
	v_add_f32_e32 v158, v158, v159
	v_add_f32_e32 v160, v160, v161
	v_add_f32_e32 v221, v158, v160
	s_waitcnt vmcnt(3)
	v_add_f32_e32 v182, v182, v183
	v_add_f32_e32 v184, v184, v185
	v_add_f32_e32 v222, v182, v184
	s_waitcnt vmcnt(2)
	v_add_f32_e32 v186, v186, v187
	v_add_f32_e32 v188, v188, v189
	v_add_f32_e32 v223, v186, v188
	s_waitcnt vmcnt(1)
	v_add_f32_e32 v190, v190, v191
	v_add_f32_e32 v192, v192, v193
	v_add_f32_e32 v224, v190, v192
	s_waitcnt vmcnt(0)
	v_add_f32_e32 v194, v194, v195
	v_add_f32_e32 v196, v196, v197
	v_add_f32_e32 v225, v194, v196
	ds_bpermute_b32 v249, v198, v218
	ds_bpermute_b32 v250, v198, v219
	ds_bpermute_b32 v251, v198, v220
	ds_bpermute_b32 v226, v198, v221
	ds_bpermute_b32 v162, v198, v222
	ds_bpermute_b32 v163, v198, v223
	ds_bpermute_b32 v164, v198, v224
	ds_bpermute_b32 v165, v198, v225
	s_waitcnt lgkmcnt(7)
	v_add_f32_e32 v218, v218, v249
	s_waitcnt lgkmcnt(6)
	v_add_f32_e32 v219, v219, v250
	s_waitcnt lgkmcnt(5)
	v_add_f32_e32 v220, v220, v251
	s_waitcnt lgkmcnt(4)
	v_add_f32_e32 v221, v221, v226
	s_waitcnt lgkmcnt(3)
	v_add_f32_e32 v222, v222, v162
	s_waitcnt lgkmcnt(2)
	v_add_f32_e32 v223, v223, v163
	s_waitcnt lgkmcnt(1)
	v_add_f32_e32 v224, v224, v164
	s_waitcnt lgkmcnt(0)
	v_add_f32_e32 v225, v225, v165
	ds_bpermute_b32 v249, v199, v218
	ds_bpermute_b32 v250, v199, v219
	ds_bpermute_b32 v251, v199, v220
	ds_bpermute_b32 v226, v199, v221
	ds_bpermute_b32 v162, v199, v222
	ds_bpermute_b32 v163, v199, v223
	ds_bpermute_b32 v164, v199, v224
	ds_bpermute_b32 v165, v199, v225
	s_waitcnt lgkmcnt(7)
	v_add_f32_e32 v218, v218, v249
	s_waitcnt lgkmcnt(6)
	v_add_f32_e32 v219, v219, v250
	s_waitcnt lgkmcnt(5)
	v_add_f32_e32 v220, v220, v251
	s_waitcnt lgkmcnt(4)
	v_add_f32_e32 v221, v221, v226
	s_waitcnt lgkmcnt(3)
	v_add_f32_e32 v222, v222, v162
	s_waitcnt lgkmcnt(2)
	v_add_f32_e32 v223, v223, v163
	s_waitcnt lgkmcnt(1)
	v_add_f32_e32 v224, v224, v164
	s_waitcnt lgkmcnt(0)
	v_add_f32_e32 v225, v225, v165
	v_fmamk_f32 v218, v218, 0x3a800000, v174
	v_fmamk_f32 v219, v219, 0x3a800000, v174
	v_fmamk_f32 v220, v220, 0x3a800000, v174
	v_fmamk_f32 v221, v221, 0x3a800000, v174
	v_fmamk_f32 v222, v222, 0x3a800000, v174
	v_fmamk_f32 v223, v223, 0x3a800000, v174
	v_fmamk_f32 v224, v224, 0x3a800000, v174
	v_fmamk_f32 v225, v225, 0x3a800000, v174
	v_rsq_f32_e32 v218, v218
	v_rsq_f32_e32 v219, v219
	v_rsq_f32_e32 v220, v220
	v_rsq_f32_e32 v221, v221
	v_rsq_f32_e32 v222, v222
	v_rsq_f32_e32 v223, v223
	v_rsq_f32_e32 v224, v224
	v_rsq_f32_e32 v225, v225
	s_mov_b32 s34, 0x3db8aa3b
	v_mul_f32_e32 v218, s34, v218
	v_mul_f32_e32 v219, s34, v219
	v_mul_f32_e32 v220, s34, v220
	v_mul_f32_e32 v221, s34, v221
	v_mul_f32_e32 v222, s34, v222
	v_mul_f32_e32 v223, s34, v223
	v_mul_f32_e32 v224, s34, v224
	v_mul_f32_e32 v225, s34, v225
	v_mul_f32_e32 v202, v202, v218
	v_mul_f32_e32 v204, v204, v219
	v_mul_f32_e32 v206, v206, v220
	v_mul_f32_e32 v208, v208, v221
	v_mul_f32_e32 v210, v210, v222
	v_mul_f32_e32 v212, v212, v223
	v_mul_f32_e32 v214, v214, v224
	v_mul_f32_e32 v216, v216, v225
	v_pk_fma_f32 v[124:125], v[124:125], v[218:219], v[202:203] op_sel:[0,0,0] op_sel_hi:[1,0,0] neg_lo:[0,0,1] neg_hi:[0,0,1]
	v_pk_fma_f32 v[126:127], v[126:127], v[218:219], v[202:203] op_sel:[0,0,0] op_sel_hi:[1,0,0] neg_lo:[0,0,1] neg_hi:[0,0,1]
	v_pk_fma_f32 v[120:121], v[120:121], v[218:219], v[202:203] op_sel:[0,0,0] op_sel_hi:[1,0,0] neg_lo:[0,0,1] neg_hi:[0,0,1]
	v_pk_fma_f32 v[122:123], v[122:123], v[218:219], v[202:203] op_sel:[0,0,0] op_sel_hi:[1,0,0] neg_lo:[0,0,1] neg_hi:[0,0,1]
	v_pk_fma_f32 v[116:117], v[116:117], v[218:219], v[202:203] op_sel:[0,0,0] op_sel_hi:[1,0,0] neg_lo:[0,0,1] neg_hi:[0,0,1]
	v_pk_fma_f32 v[118:119], v[118:119], v[218:219], v[202:203] op_sel:[0,0,0] op_sel_hi:[1,0,0] neg_lo:[0,0,1] neg_hi:[0,0,1]
	v_pk_fma_f32 v[112:113], v[112:113], v[218:219], v[202:203] op_sel:[0,0,0] op_sel_hi:[1,0,0] neg_lo:[0,0,1] neg_hi:[0,0,1]
	v_pk_fma_f32 v[114:115], v[114:115], v[218:219], v[202:203] op_sel:[0,0,0] op_sel_hi:[1,0,0] neg_lo:[0,0,1] neg_hi:[0,0,1]
	v_exp_f32_e32 v124, v124
	v_exp_f32_e32 v125, v125
	v_exp_f32_e32 v126, v126
	v_exp_f32_e32 v127, v127
	v_exp_f32_e32 v120, v120
	v_exp_f32_e32 v121, v121
	v_exp_f32_e32 v122, v122
	v_exp_f32_e32 v123, v123
	v_exp_f32_e32 v116, v116
	v_exp_f32_e32 v117, v117
	v_exp_f32_e32 v118, v118
	v_exp_f32_e32 v119, v119
	v_exp_f32_e32 v112, v112
	v_exp_f32_e32 v113, v113
	v_exp_f32_e32 v114, v114
	v_exp_f32_e32 v115, v115
	v_pk_add_f32 v[162:163], v[124:125], v[126:127]
	v_pk_add_f32 v[164:165], v[120:121], v[122:123]
	v_pk_add_f32 v[252:253], v[116:117], v[118:119]
	v_pk_add_f32 v[254:255], v[112:113], v[114:115]
	v_pk_add_f32 v[162:163], v[162:163], v[164:165]
	v_pk_add_f32 v[252:253], v[252:253], v[254:255]
	v_pk_add_f32 v[162:163], v[162:163], v[252:253]
	v_add_f32_e32 v203, v162, v163
	v_pk_fma_f32 v[108:109], v[108:109], v[218:219], v[204:205] op_sel:[0,1,0] op_sel_hi:[1,1,0] neg_lo:[0,0,1] neg_hi:[0,0,1]
	v_pk_fma_f32 v[110:111], v[110:111], v[218:219], v[204:205] op_sel:[0,1,0] op_sel_hi:[1,1,0] neg_lo:[0,0,1] neg_hi:[0,0,1]
	v_pk_fma_f32 v[104:105], v[104:105], v[218:219], v[204:205] op_sel:[0,1,0] op_sel_hi:[1,1,0] neg_lo:[0,0,1] neg_hi:[0,0,1]
	v_pk_fma_f32 v[106:107], v[106:107], v[218:219], v[204:205] op_sel:[0,1,0] op_sel_hi:[1,1,0] neg_lo:[0,0,1] neg_hi:[0,0,1]
	v_pk_fma_f32 v[100:101], v[100:101], v[218:219], v[204:205] op_sel:[0,1,0] op_sel_hi:[1,1,0] neg_lo:[0,0,1] neg_hi:[0,0,1]
	v_pk_fma_f32 v[102:103], v[102:103], v[218:219], v[204:205] op_sel:[0,1,0] op_sel_hi:[1,1,0] neg_lo:[0,0,1] neg_hi:[0,0,1]
	v_pk_fma_f32 v[96:97], v[96:97], v[218:219], v[204:205] op_sel:[0,1,0] op_sel_hi:[1,1,0] neg_lo:[0,0,1] neg_hi:[0,0,1]
	v_pk_fma_f32 v[98:99], v[98:99], v[218:219], v[204:205] op_sel:[0,1,0] op_sel_hi:[1,1,0] neg_lo:[0,0,1] neg_hi:[0,0,1]
	v_exp_f32_e32 v108, v108
	v_exp_f32_e32 v109, v109
	v_exp_f32_e32 v110, v110
	v_exp_f32_e32 v111, v111
	v_exp_f32_e32 v104, v104
	v_exp_f32_e32 v105, v105
	v_exp_f32_e32 v106, v106
	v_exp_f32_e32 v107, v107
	v_exp_f32_e32 v100, v100
	v_exp_f32_e32 v101, v101
	v_exp_f32_e32 v102, v102
	v_exp_f32_e32 v103, v103
	v_exp_f32_e32 v96, v96
	v_exp_f32_e32 v97, v97
	v_exp_f32_e32 v98, v98
	v_exp_f32_e32 v99, v99
	v_pk_add_f32 v[162:163], v[108:109], v[110:111]
	v_pk_add_f32 v[164:165], v[104:105], v[106:107]
	v_pk_add_f32 v[252:253], v[100:101], v[102:103]
	v_pk_add_f32 v[254:255], v[96:97], v[98:99]
	v_pk_add_f32 v[162:163], v[162:163], v[164:165]
	v_pk_add_f32 v[252:253], v[252:253], v[254:255]
	v_pk_add_f32 v[162:163], v[162:163], v[252:253]
	v_add_f32_e32 v205, v162, v163
	ds_bpermute_b32 v249, v198, v203
	ds_bpermute_b32 v250, v198, v205
	v_pk_fma_f32 v[92:93], v[92:93], v[220:221], v[206:207] op_sel:[0,0,0] op_sel_hi:[1,0,0] neg_lo:[0,0,1] neg_hi:[0,0,1]
	v_pk_fma_f32 v[94:95], v[94:95], v[220:221], v[206:207] op_sel:[0,0,0] op_sel_hi:[1,0,0] neg_lo:[0,0,1] neg_hi:[0,0,1]
	v_pk_fma_f32 v[88:89], v[88:89], v[220:221], v[206:207] op_sel:[0,0,0] op_sel_hi:[1,0,0] neg_lo:[0,0,1] neg_hi:[0,0,1]
	v_pk_fma_f32 v[90:91], v[90:91], v[220:221], v[206:207] op_sel:[0,0,0] op_sel_hi:[1,0,0] neg_lo:[0,0,1] neg_hi:[0,0,1]
	v_pk_fma_f32 v[84:85], v[84:85], v[220:221], v[206:207] op_sel:[0,0,0] op_sel_hi:[1,0,0] neg_lo:[0,0,1] neg_hi:[0,0,1]
	v_pk_fma_f32 v[86:87], v[86:87], v[220:221], v[206:207] op_sel:[0,0,0] op_sel_hi:[1,0,0] neg_lo:[0,0,1] neg_hi:[0,0,1]
	v_pk_fma_f32 v[80:81], v[80:81], v[220:221], v[206:207] op_sel:[0,0,0] op_sel_hi:[1,0,0] neg_lo:[0,0,1] neg_hi:[0,0,1]
	v_pk_fma_f32 v[82:83], v[82:83], v[220:221], v[206:207] op_sel:[0,0,0] op_sel_hi:[1,0,0] neg_lo:[0,0,1] neg_hi:[0,0,1]
	v_exp_f32_e32 v92, v92
	v_exp_f32_e32 v93, v93
	v_exp_f32_e32 v94, v94
	v_exp_f32_e32 v95, v95
	v_exp_f32_e32 v88, v88
	v_exp_f32_e32 v89, v89
	v_exp_f32_e32 v90, v90
	v_exp_f32_e32 v91, v91
	s_waitcnt lgkmcnt(1)
	v_add_f32_e32 v203, v203, v249
	s_waitcnt lgkmcnt(0)
	v_add_f32_e32 v205, v205, v250
	ds_bpermute_b32 v249, v199, v203
	ds_bpermute_b32 v250, v199, v205
	v_exp_f32_e32 v84, v84
	v_exp_f32_e32 v85, v85
	v_exp_f32_e32 v86, v86
	v_exp_f32_e32 v87, v87
	v_exp_f32_e32 v80, v80
	v_exp_f32_e32 v81, v81
	v_exp_f32_e32 v82, v82
	v_exp_f32_e32 v83, v83
	v_pk_add_f32 v[162:163], v[92:93], v[94:95]
	v_pk_add_f32 v[164:165], v[88:89], v[90:91]
	v_pk_add_f32 v[252:253], v[84:85], v[86:87]
	v_pk_add_f32 v[254:255], v[80:81], v[82:83]
	v_pk_add_f32 v[162:163], v[162:163], v[164:165]
	v_pk_add_f32 v[252:253], v[252:253], v[254:255]
	v_pk_add_f32 v[162:163], v[162:163], v[252:253]
	v_add_f32_e32 v207, v162, v163
	s_waitcnt lgkmcnt(1)
	v_add_f32_e32 v203, v203, v249
	s_waitcnt lgkmcnt(0)
	v_add_f32_e32 v205, v205, v250
	s_mov_b64 vcc, exec
	s_and_b64 exec, exec, s[0:1]
	ds_write_b64 v201, v[202:203]
	ds_write_b64 v175, v[204:205]
	s_mov_b64 exec, vcc
	v_pk_fma_f32 v[76:77], v[76:77], v[220:221], v[208:209] op_sel:[0,1,0] op_sel_hi:[1,1,0] neg_lo:[0,0,1] neg_hi:[0,0,1]
	v_pk_fma_f32 v[78:79], v[78:79], v[220:221], v[208:209] op_sel:[0,1,0] op_sel_hi:[1,1,0] neg_lo:[0,0,1] neg_hi:[0,0,1]
	v_pk_fma_f32 v[72:73], v[72:73], v[220:221], v[208:209] op_sel:[0,1,0] op_sel_hi:[1,1,0] neg_lo:[0,0,1] neg_hi:[0,0,1]
	v_pk_fma_f32 v[74:75], v[74:75], v[220:221], v[208:209] op_sel:[0,1,0] op_sel_hi:[1,1,0] neg_lo:[0,0,1] neg_hi:[0,0,1]
	v_pk_fma_f32 v[68:69], v[68:69], v[220:221], v[208:209] op_sel:[0,1,0] op_sel_hi:[1,1,0] neg_lo:[0,0,1] neg_hi:[0,0,1]
	v_pk_fma_f32 v[70:71], v[70:71], v[220:221], v[208:209] op_sel:[0,1,0] op_sel_hi:[1,1,0] neg_lo:[0,0,1] neg_hi:[0,0,1]
	v_pk_fma_f32 v[64:65], v[64:65], v[220:221], v[208:209] op_sel:[0,1,0] op_sel_hi:[1,1,0] neg_lo:[0,0,1] neg_hi:[0,0,1]
	v_pk_fma_f32 v[66:67], v[66:67], v[220:221], v[208:209] op_sel:[0,1,0] op_sel_hi:[1,1,0] neg_lo:[0,0,1] neg_hi:[0,0,1]
	v_exp_f32_e32 v76, v76
	v_exp_f32_e32 v77, v77
	v_exp_f32_e32 v78, v78
	v_exp_f32_e32 v79, v79
	v_exp_f32_e32 v72, v72
	v_exp_f32_e32 v73, v73
	v_exp_f32_e32 v74, v74
	v_exp_f32_e32 v75, v75
	s_waitcnt lgkmcnt(0)
	s_barrier
	ds_read_b128 v[146:149], v168
	ds_read_b128 v[150:153], v168 offset:16
	ds_read_b128 v[154:157], v168 offset:512
	ds_read_b128 v[158:161], v168 offset:528
	v_exp_f32_e32 v68, v68
	v_exp_f32_e32 v69, v69
	v_exp_f32_e32 v70, v70
	v_exp_f32_e32 v71, v71
	v_exp_f32_e32 v64, v64
	v_exp_f32_e32 v65, v65
	v_exp_f32_e32 v66, v66
	v_exp_f32_e32 v67, v67
	v_pk_add_f32 v[162:163], v[76:77], v[78:79]
	v_pk_add_f32 v[164:165], v[72:73], v[74:75]
	v_pk_add_f32 v[252:253], v[68:69], v[70:71]
	v_pk_add_f32 v[254:255], v[64:65], v[66:67]
	v_pk_add_f32 v[162:163], v[162:163], v[164:165]
	v_pk_add_f32 v[252:253], v[252:253], v[254:255]
	v_pk_add_f32 v[162:163], v[162:163], v[252:253]
	v_add_f32_e32 v209, v162, v163
	s_waitcnt lgkmcnt(2)
	v_max3_f32 v227, v146, v148, v150
	v_max_f32_e32 v227, v227, v152
	v_sub_f32_e32 v146, v146, v227
	v_sub_f32_e32 v148, v148, v227
	v_sub_f32_e32 v150, v150, v227
	v_sub_f32_e32 v152, v152, v227
	v_sub_f32_e32 v202, v202, v227
	v_exp_f32_e32 v146, v146
	v_exp_f32_e32 v148, v148
	v_exp_f32_e32 v150, v150
	v_exp_f32_e32 v152, v152
	v_exp_f32_e32 v202, v202
	v_mul_f32_e32 v228, v147, v146
	v_mul_f32_e32 v226, v151, v150
	v_fmac_f32_e32 v228, v149, v148
	v_fmac_f32_e32 v226, v153, v152
	v_add_f32_e32 v228, v228, v226
	v_rcp_f32_e32 v228, v228
	s_nop 0
	v_mul_f32_e32 v202, v202, v228
	s_mov_b32 s34, 0x0
	v_pk_mul_f32 v[124:125], v[124:125], v[202:203] op_sel:[0,0] op_sel_hi:[1,0]
	v_pk_mul_f32 v[126:127], v[126:127], v[202:203] op_sel:[0,0] op_sel_hi:[1,0]
	v_pk_mul_f32 v[120:121], v[120:121], v[202:203] op_sel:[0,0] op_sel_hi:[1,0]
	v_pk_mul_f32 v[122:123], v[122:123], v[202:203] op_sel:[0,0] op_sel_hi:[1,0]
	v_cvt_pk_bf16_f32 v124, v124, v125
	v_cvt_pk_bf16_f32 v125, v126, v127
	v_cvt_pk_bf16_f32 v126, v120, v121
	v_cvt_pk_bf16_f32 v127, v122, v123
	buffer_store_dwordx4 v[124:127], v229, s[16:19], s34 offen sc1
	v_pk_mul_f32 v[116:117], v[116:117], v[202:203] op_sel:[0,0] op_sel_hi:[1,0]
	v_pk_mul_f32 v[118:119], v[118:119], v[202:203] op_sel:[0,0] op_sel_hi:[1,0]
	v_pk_mul_f32 v[112:113], v[112:113], v[202:203] op_sel:[0,0] op_sel_hi:[1,0]
	v_pk_mul_f32 v[114:115], v[114:115], v[202:203] op_sel:[0,0] op_sel_hi:[1,0]
	v_cvt_pk_bf16_f32 v116, v116, v117
	v_cvt_pk_bf16_f32 v117, v118, v119
	v_cvt_pk_bf16_f32 v118, v112, v113
	v_cvt_pk_bf16_f32 v119, v114, v115
	buffer_store_dwordx4 v[116:119], v229, s[16:19], s34 offen offset:256 sc1
	s_waitcnt lgkmcnt(0)
	v_max3_f32 v227, v154, v156, v158
	v_max_f32_e32 v227, v227, v160
	v_sub_f32_e32 v154, v154, v227
	v_sub_f32_e32 v156, v156, v227
	v_sub_f32_e32 v158, v158, v227
	v_sub_f32_e32 v160, v160, v227
	v_sub_f32_e32 v204, v204, v227
	v_exp_f32_e32 v154, v154
	v_exp_f32_e32 v156, v156
	v_exp_f32_e32 v158, v158
	v_exp_f32_e32 v160, v160
	v_exp_f32_e32 v204, v204
	v_mul_f32_e32 v228, v155, v154
	v_mul_f32_e32 v226, v159, v158
	v_fmac_f32_e32 v228, v157, v156
	v_fmac_f32_e32 v226, v161, v160
	v_add_f32_e32 v228, v228, v226
	v_rcp_f32_e32 v228, v228
	s_nop 0
	v_mul_f32_e32 v204, v204, v228
	s_mov_b32 s34, 0x8000
	v_pk_mul_f32 v[108:109], v[108:109], v[204:205] op_sel:[0,0] op_sel_hi:[1,0]
	v_pk_mul_f32 v[110:111], v[110:111], v[204:205] op_sel:[0,0] op_sel_hi:[1,0]
	v_pk_mul_f32 v[104:105], v[104:105], v[204:205] op_sel:[0,0] op_sel_hi:[1,0]
	v_pk_mul_f32 v[106:107], v[106:107], v[204:205] op_sel:[0,0] op_sel_hi:[1,0]
	v_cvt_pk_bf16_f32 v108, v108, v109
	v_cvt_pk_bf16_f32 v109, v110, v111
	v_cvt_pk_bf16_f32 v110, v104, v105
	v_cvt_pk_bf16_f32 v111, v106, v107
	buffer_store_dwordx4 v[108:111], v229, s[16:19], s34 offen sc1
	v_pk_mul_f32 v[100:101], v[100:101], v[204:205] op_sel:[0,0] op_sel_hi:[1,0]
	v_pk_mul_f32 v[102:103], v[102:103], v[204:205] op_sel:[0,0] op_sel_hi:[1,0]
	v_pk_mul_f32 v[96:97], v[96:97], v[204:205] op_sel:[0,0] op_sel_hi:[1,0]
	v_pk_mul_f32 v[98:99], v[98:99], v[204:205] op_sel:[0,0] op_sel_hi:[1,0]
	v_cvt_pk_bf16_f32 v100, v100, v101
	v_cvt_pk_bf16_f32 v101, v102, v103
	v_cvt_pk_bf16_f32 v102, v96, v97
	v_cvt_pk_bf16_f32 v103, v98, v99
	buffer_store_dwordx4 v[100:103], v229, s[16:19], s34 offen offset:256 sc1
	ds_bpermute_b32 v249, v198, v207
	ds_bpermute_b32 v250, v198, v209
	v_pk_fma_f32 v[60:61], v[60:61], v[222:223], v[210:211] op_sel:[0,0,0] op_sel_hi:[1,0,0] neg_lo:[0,0,1] neg_hi:[0,0,1]
	v_pk_fma_f32 v[62:63], v[62:63], v[222:223], v[210:211] op_sel:[0,0,0] op_sel_hi:[1,0,0] neg_lo:[0,0,1] neg_hi:[0,0,1]
	v_pk_fma_f32 v[56:57], v[56:57], v[222:223], v[210:211] op_sel:[0,0,0] op_sel_hi:[1,0,0] neg_lo:[0,0,1] neg_hi:[0,0,1]
	v_pk_fma_f32 v[58:59], v[58:59], v[222:223], v[210:211] op_sel:[0,0,0] op_sel_hi:[1,0,0] neg_lo:[0,0,1] neg_hi:[0,0,1]
	v_pk_fma_f32 v[52:53], v[52:53], v[222:223], v[210:211] op_sel:[0,0,0] op_sel_hi:[1,0,0] neg_lo:[0,0,1] neg_hi:[0,0,1]
	v_pk_fma_f32 v[54:55], v[54:55], v[222:223], v[210:211] op_sel:[0,0,0] op_sel_hi:[1,0,0] neg_lo:[0,0,1] neg_hi:[0,0,1]
	v_pk_fma_f32 v[48:49], v[48:49], v[222:223], v[210:211] op_sel:[0,0,0] op_sel_hi:[1,0,0] neg_lo:[0,0,1] neg_hi:[0,0,1]
	v_pk_fma_f32 v[50:51], v[50:51], v[222:223], v[210:211] op_sel:[0,0,0] op_sel_hi:[1,0,0] neg_lo:[0,0,1] neg_hi:[0,0,1]
	v_exp_f32_e32 v60, v60
	v_exp_f32_e32 v61, v61
	v_exp_f32_e32 v62, v62
	v_exp_f32_e32 v63, v63
	v_exp_f32_e32 v56, v56
	v_exp_f32_e32 v57, v57
	v_exp_f32_e32 v58, v58
	v_exp_f32_e32 v59, v59
	s_waitcnt lgkmcnt(1)
	v_add_f32_e32 v207, v207, v249
	s_waitcnt lgkmcnt(0)
	v_add_f32_e32 v209, v209, v250
	ds_bpermute_b32 v249, v199, v207
	ds_bpermute_b32 v250, v199, v209
	v_exp_f32_e32 v52, v52
	v_exp_f32_e32 v53, v53
	v_exp_f32_e32 v54, v54
	v_exp_f32_e32 v55, v55
	v_exp_f32_e32 v48, v48
	v_exp_f32_e32 v49, v49
	v_exp_f32_e32 v50, v50
	v_exp_f32_e32 v51, v51
	v_pk_add_f32 v[162:163], v[60:61], v[62:63]
	v_pk_add_f32 v[164:165], v[56:57], v[58:59]
	v_pk_add_f32 v[252:253], v[52:53], v[54:55]
	v_pk_add_f32 v[254:255], v[48:49], v[50:51]
	v_pk_add_f32 v[162:163], v[162:163], v[164:165]
	v_pk_add_f32 v[252:253], v[252:253], v[254:255]
	v_pk_add_f32 v[162:163], v[162:163], v[252:253]
	v_add_f32_e32 v211, v162, v163
	s_waitcnt lgkmcnt(1)
	v_add_f32_e32 v207, v207, v249
	s_waitcnt lgkmcnt(0)
	v_add_f32_e32 v209, v209, v250
	s_mov_b64 vcc, exec
	s_and_b64 exec, exec, s[0:1]
	ds_write_b64 v176, v[206:207]
	ds_write_b64 v177, v[208:209]
	s_mov_b64 exec, vcc
	v_pk_fma_f32 v[44:45], v[44:45], v[222:223], v[212:213] op_sel:[0,1,0] op_sel_hi:[1,1,0] neg_lo:[0,0,1] neg_hi:[0,0,1]
	v_pk_fma_f32 v[46:47], v[46:47], v[222:223], v[212:213] op_sel:[0,1,0] op_sel_hi:[1,1,0] neg_lo:[0,0,1] neg_hi:[0,0,1]
	v_pk_fma_f32 v[40:41], v[40:41], v[222:223], v[212:213] op_sel:[0,1,0] op_sel_hi:[1,1,0] neg_lo:[0,0,1] neg_hi:[0,0,1]
	v_pk_fma_f32 v[42:43], v[42:43], v[222:223], v[212:213] op_sel:[0,1,0] op_sel_hi:[1,1,0] neg_lo:[0,0,1] neg_hi:[0,0,1]
	v_pk_fma_f32 v[36:37], v[36:37], v[222:223], v[212:213] op_sel:[0,1,0] op_sel_hi:[1,1,0] neg_lo:[0,0,1] neg_hi:[0,0,1]
	v_pk_fma_f32 v[38:39], v[38:39], v[222:223], v[212:213] op_sel:[0,1,0] op_sel_hi:[1,1,0] neg_lo:[0,0,1] neg_hi:[0,0,1]
	v_pk_fma_f32 v[32:33], v[32:33], v[222:223], v[212:213] op_sel:[0,1,0] op_sel_hi:[1,1,0] neg_lo:[0,0,1] neg_hi:[0,0,1]
	v_pk_fma_f32 v[34:35], v[34:35], v[222:223], v[212:213] op_sel:[0,1,0] op_sel_hi:[1,1,0] neg_lo:[0,0,1] neg_hi:[0,0,1]
	v_exp_f32_e32 v44, v44
	v_exp_f32_e32 v45, v45
	v_exp_f32_e32 v46, v46
	v_exp_f32_e32 v47, v47
	v_exp_f32_e32 v40, v40
	v_exp_f32_e32 v41, v41
	v_exp_f32_e32 v42, v42
	v_exp_f32_e32 v43, v43
	s_waitcnt lgkmcnt(0)
	s_barrier
	ds_read_b128 v[146:149], v168 offset:1024
	ds_read_b128 v[150:153], v168 offset:1040
	ds_read_b128 v[154:157], v168 offset:1536
	ds_read_b128 v[158:161], v168 offset:1552
	v_exp_f32_e32 v36, v36
	v_exp_f32_e32 v37, v37
	v_exp_f32_e32 v38, v38
	v_exp_f32_e32 v39, v39
	v_exp_f32_e32 v32, v32
	v_exp_f32_e32 v33, v33
	v_exp_f32_e32 v34, v34
	v_exp_f32_e32 v35, v35
	v_pk_add_f32 v[162:163], v[44:45], v[46:47]
	v_pk_add_f32 v[164:165], v[40:41], v[42:43]
	v_pk_add_f32 v[252:253], v[36:37], v[38:39]
	v_pk_add_f32 v[254:255], v[32:33], v[34:35]
	v_pk_add_f32 v[162:163], v[162:163], v[164:165]
	v_pk_add_f32 v[252:253], v[252:253], v[254:255]
	v_pk_add_f32 v[162:163], v[162:163], v[252:253]
	v_add_f32_e32 v213, v162, v163
	s_waitcnt lgkmcnt(2)
	v_max3_f32 v227, v146, v148, v150
	v_max_f32_e32 v227, v227, v152
	v_sub_f32_e32 v146, v146, v227
	v_sub_f32_e32 v148, v148, v227
	v_sub_f32_e32 v150, v150, v227
	v_sub_f32_e32 v152, v152, v227
	v_sub_f32_e32 v206, v206, v227
	v_exp_f32_e32 v146, v146
	v_exp_f32_e32 v148, v148
	v_exp_f32_e32 v150, v150
	v_exp_f32_e32 v152, v152
	v_exp_f32_e32 v206, v206
	v_mul_f32_e32 v228, v147, v146
	v_mul_f32_e32 v226, v151, v150
	v_fmac_f32_e32 v228, v149, v148
	v_fmac_f32_e32 v226, v153, v152
	v_add_f32_e32 v228, v228, v226
	v_rcp_f32_e32 v228, v228
	s_nop 0
	v_mul_f32_e32 v206, v206, v228
	s_mov_b32 s34, 0x10000
	v_pk_mul_f32 v[92:93], v[92:93], v[206:207] op_sel:[0,0] op_sel_hi:[1,0]
	v_pk_mul_f32 v[94:95], v[94:95], v[206:207] op_sel:[0,0] op_sel_hi:[1,0]
	v_pk_mul_f32 v[88:89], v[88:89], v[206:207] op_sel:[0,0] op_sel_hi:[1,0]
	v_pk_mul_f32 v[90:91], v[90:91], v[206:207] op_sel:[0,0] op_sel_hi:[1,0]
	v_cvt_pk_bf16_f32 v92, v92, v93
	v_cvt_pk_bf16_f32 v93, v94, v95
	v_cvt_pk_bf16_f32 v94, v88, v89
	v_cvt_pk_bf16_f32 v95, v90, v91
	buffer_store_dwordx4 v[92:95], v229, s[16:19], s34 offen sc1
	v_pk_mul_f32 v[84:85], v[84:85], v[206:207] op_sel:[0,0] op_sel_hi:[1,0]
	v_pk_mul_f32 v[86:87], v[86:87], v[206:207] op_sel:[0,0] op_sel_hi:[1,0]
	v_pk_mul_f32 v[80:81], v[80:81], v[206:207] op_sel:[0,0] op_sel_hi:[1,0]
	v_pk_mul_f32 v[82:83], v[82:83], v[206:207] op_sel:[0,0] op_sel_hi:[1,0]
	v_cvt_pk_bf16_f32 v84, v84, v85
	v_cvt_pk_bf16_f32 v85, v86, v87
	v_cvt_pk_bf16_f32 v86, v80, v81
	v_cvt_pk_bf16_f32 v87, v82, v83
	buffer_store_dwordx4 v[84:87], v229, s[16:19], s34 offen offset:256 sc1
	s_waitcnt lgkmcnt(0)
	v_max3_f32 v227, v154, v156, v158
	v_max_f32_e32 v227, v227, v160
	v_sub_f32_e32 v154, v154, v227
	v_sub_f32_e32 v156, v156, v227
	v_sub_f32_e32 v158, v158, v227
	v_sub_f32_e32 v160, v160, v227
	v_sub_f32_e32 v208, v208, v227
	v_exp_f32_e32 v154, v154
	v_exp_f32_e32 v156, v156
	v_exp_f32_e32 v158, v158
	v_exp_f32_e32 v160, v160
	v_exp_f32_e32 v208, v208
	v_mul_f32_e32 v228, v155, v154
	v_mul_f32_e32 v226, v159, v158
	v_fmac_f32_e32 v228, v157, v156
	v_fmac_f32_e32 v226, v161, v160
	v_add_f32_e32 v228, v228, v226
	v_rcp_f32_e32 v228, v228
	s_nop 0
	v_mul_f32_e32 v208, v208, v228
	s_mov_b32 s34, 0x18000
	v_pk_mul_f32 v[76:77], v[76:77], v[208:209] op_sel:[0,0] op_sel_hi:[1,0]
	v_pk_mul_f32 v[78:79], v[78:79], v[208:209] op_sel:[0,0] op_sel_hi:[1,0]
	v_pk_mul_f32 v[72:73], v[72:73], v[208:209] op_sel:[0,0] op_sel_hi:[1,0]
	v_pk_mul_f32 v[74:75], v[74:75], v[208:209] op_sel:[0,0] op_sel_hi:[1,0]
	v_cvt_pk_bf16_f32 v76, v76, v77
	v_cvt_pk_bf16_f32 v77, v78, v79
	v_cvt_pk_bf16_f32 v78, v72, v73
	v_cvt_pk_bf16_f32 v79, v74, v75
	buffer_store_dwordx4 v[76:79], v229, s[16:19], s34 offen sc1
	v_pk_mul_f32 v[68:69], v[68:69], v[208:209] op_sel:[0,0] op_sel_hi:[1,0]
	v_pk_mul_f32 v[70:71], v[70:71], v[208:209] op_sel:[0,0] op_sel_hi:[1,0]
	v_pk_mul_f32 v[64:65], v[64:65], v[208:209] op_sel:[0,0] op_sel_hi:[1,0]
	v_pk_mul_f32 v[66:67], v[66:67], v[208:209] op_sel:[0,0] op_sel_hi:[1,0]
	v_cvt_pk_bf16_f32 v68, v68, v69
	v_cvt_pk_bf16_f32 v69, v70, v71
	v_cvt_pk_bf16_f32 v70, v64, v65
	v_cvt_pk_bf16_f32 v71, v66, v67
	buffer_store_dwordx4 v[68:71], v229, s[16:19], s34 offen offset:256 sc1
	ds_bpermute_b32 v249, v198, v211
	ds_bpermute_b32 v250, v198, v213
	v_pk_fma_f32 v[28:29], v[28:29], v[224:225], v[214:215] op_sel:[0,0,0] op_sel_hi:[1,0,0] neg_lo:[0,0,1] neg_hi:[0,0,1]
	v_pk_fma_f32 v[30:31], v[30:31], v[224:225], v[214:215] op_sel:[0,0,0] op_sel_hi:[1,0,0] neg_lo:[0,0,1] neg_hi:[0,0,1]
	v_pk_fma_f32 v[24:25], v[24:25], v[224:225], v[214:215] op_sel:[0,0,0] op_sel_hi:[1,0,0] neg_lo:[0,0,1] neg_hi:[0,0,1]
	v_pk_fma_f32 v[26:27], v[26:27], v[224:225], v[214:215] op_sel:[0,0,0] op_sel_hi:[1,0,0] neg_lo:[0,0,1] neg_hi:[0,0,1]
	v_pk_fma_f32 v[20:21], v[20:21], v[224:225], v[214:215] op_sel:[0,0,0] op_sel_hi:[1,0,0] neg_lo:[0,0,1] neg_hi:[0,0,1]
	v_pk_fma_f32 v[22:23], v[22:23], v[224:225], v[214:215] op_sel:[0,0,0] op_sel_hi:[1,0,0] neg_lo:[0,0,1] neg_hi:[0,0,1]
	v_pk_fma_f32 v[16:17], v[16:17], v[224:225], v[214:215] op_sel:[0,0,0] op_sel_hi:[1,0,0] neg_lo:[0,0,1] neg_hi:[0,0,1]
	v_pk_fma_f32 v[18:19], v[18:19], v[224:225], v[214:215] op_sel:[0,0,0] op_sel_hi:[1,0,0] neg_lo:[0,0,1] neg_hi:[0,0,1]
	v_exp_f32_e32 v28, v28
	v_exp_f32_e32 v29, v29
	v_exp_f32_e32 v30, v30
	v_exp_f32_e32 v31, v31
	v_exp_f32_e32 v24, v24
	v_exp_f32_e32 v25, v25
	v_exp_f32_e32 v26, v26
	v_exp_f32_e32 v27, v27
	s_waitcnt lgkmcnt(1)
	v_add_f32_e32 v211, v211, v249
	s_waitcnt lgkmcnt(0)
	v_add_f32_e32 v213, v213, v250
	ds_bpermute_b32 v249, v199, v211
	ds_bpermute_b32 v250, v199, v213
	v_exp_f32_e32 v20, v20
	v_exp_f32_e32 v21, v21
	v_exp_f32_e32 v22, v22
	v_exp_f32_e32 v23, v23
	v_exp_f32_e32 v16, v16
	v_exp_f32_e32 v17, v17
	v_exp_f32_e32 v18, v18
	v_exp_f32_e32 v19, v19
	v_pk_add_f32 v[162:163], v[28:29], v[30:31]
	v_pk_add_f32 v[164:165], v[24:25], v[26:27]
	v_pk_add_f32 v[252:253], v[20:21], v[22:23]
	v_pk_add_f32 v[254:255], v[16:17], v[18:19]
	v_pk_add_f32 v[162:163], v[162:163], v[164:165]
	v_pk_add_f32 v[252:253], v[252:253], v[254:255]
	v_pk_add_f32 v[162:163], v[162:163], v[252:253]
	v_add_f32_e32 v215, v162, v163
	s_waitcnt lgkmcnt(1)
	v_add_f32_e32 v211, v211, v249
	s_waitcnt lgkmcnt(0)
	v_add_f32_e32 v213, v213, v250
	s_mov_b64 vcc, exec
	s_and_b64 exec, exec, s[0:1]
	ds_write_b64 v178, v[210:211]
	ds_write_b64 v179, v[212:213]
	s_mov_b64 exec, vcc
	v_pk_fma_f32 v[12:13], v[12:13], v[224:225], v[216:217] op_sel:[0,1,0] op_sel_hi:[1,1,0] neg_lo:[0,0,1] neg_hi:[0,0,1]
	v_pk_fma_f32 v[14:15], v[14:15], v[224:225], v[216:217] op_sel:[0,1,0] op_sel_hi:[1,1,0] neg_lo:[0,0,1] neg_hi:[0,0,1]
	v_pk_fma_f32 v[8:9], v[8:9], v[224:225], v[216:217] op_sel:[0,1,0] op_sel_hi:[1,1,0] neg_lo:[0,0,1] neg_hi:[0,0,1]
	v_pk_fma_f32 v[10:11], v[10:11], v[224:225], v[216:217] op_sel:[0,1,0] op_sel_hi:[1,1,0] neg_lo:[0,0,1] neg_hi:[0,0,1]
	v_pk_fma_f32 v[4:5], v[4:5], v[224:225], v[216:217] op_sel:[0,1,0] op_sel_hi:[1,1,0] neg_lo:[0,0,1] neg_hi:[0,0,1]
	v_pk_fma_f32 v[6:7], v[6:7], v[224:225], v[216:217] op_sel:[0,1,0] op_sel_hi:[1,1,0] neg_lo:[0,0,1] neg_hi:[0,0,1]
	v_pk_fma_f32 v[0:1], v[0:1], v[224:225], v[216:217] op_sel:[0,1,0] op_sel_hi:[1,1,0] neg_lo:[0,0,1] neg_hi:[0,0,1]
	v_pk_fma_f32 v[2:3], v[2:3], v[224:225], v[216:217] op_sel:[0,1,0] op_sel_hi:[1,1,0] neg_lo:[0,0,1] neg_hi:[0,0,1]
	v_exp_f32_e32 v12, v12
	v_exp_f32_e32 v13, v13
	v_exp_f32_e32 v14, v14
	v_exp_f32_e32 v15, v15
	v_exp_f32_e32 v8, v8
	v_exp_f32_e32 v9, v9
	v_exp_f32_e32 v10, v10
	v_exp_f32_e32 v11, v11
	s_waitcnt lgkmcnt(0)
	s_barrier
	ds_read_b128 v[146:149], v168 offset:4096
	ds_read_b128 v[150:153], v168 offset:4112
	ds_read_b128 v[154:157], v168 offset:4608
	ds_read_b128 v[158:161], v168 offset:4624
	v_exp_f32_e32 v4, v4
	v_exp_f32_e32 v5, v5
	v_exp_f32_e32 v6, v6
	v_exp_f32_e32 v7, v7
	v_exp_f32_e32 v0, v0
	v_exp_f32_e32 v1, v1
	v_exp_f32_e32 v2, v2
	v_exp_f32_e32 v3, v3
	v_pk_add_f32 v[162:163], v[12:13], v[14:15]
	v_pk_add_f32 v[164:165], v[8:9], v[10:11]
	v_pk_add_f32 v[252:253], v[4:5], v[6:7]
	v_pk_add_f32 v[254:255], v[0:1], v[2:3]
	v_pk_add_f32 v[162:163], v[162:163], v[164:165]
	v_pk_add_f32 v[252:253], v[252:253], v[254:255]
	v_pk_add_f32 v[162:163], v[162:163], v[252:253]
	v_add_f32_e32 v217, v162, v163
	s_waitcnt lgkmcnt(2)
	v_max3_f32 v227, v146, v148, v150
	v_max_f32_e32 v227, v227, v152
	v_sub_f32_e32 v146, v146, v227
	v_sub_f32_e32 v148, v148, v227
	v_sub_f32_e32 v150, v150, v227
	v_sub_f32_e32 v152, v152, v227
	v_sub_f32_e32 v210, v210, v227
	v_exp_f32_e32 v146, v146
	v_exp_f32_e32 v148, v148
	v_exp_f32_e32 v150, v150
	v_exp_f32_e32 v152, v152
	v_exp_f32_e32 v210, v210
	v_mul_f32_e32 v228, v147, v146
	v_mul_f32_e32 v226, v151, v150
	v_fmac_f32_e32 v228, v149, v148
	v_fmac_f32_e32 v226, v153, v152
	v_add_f32_e32 v228, v228, v226
	v_rcp_f32_e32 v228, v228
	s_nop 0
	v_mul_f32_e32 v210, v210, v228
	s_mov_b32 s34, 0x40000
	v_pk_mul_f32 v[60:61], v[60:61], v[210:211] op_sel:[0,0] op_sel_hi:[1,0]
	v_pk_mul_f32 v[62:63], v[62:63], v[210:211] op_sel:[0,0] op_sel_hi:[1,0]
	v_pk_mul_f32 v[56:57], v[56:57], v[210:211] op_sel:[0,0] op_sel_hi:[1,0]
	v_pk_mul_f32 v[58:59], v[58:59], v[210:211] op_sel:[0,0] op_sel_hi:[1,0]
	v_cvt_pk_bf16_f32 v60, v60, v61
	v_cvt_pk_bf16_f32 v61, v62, v63
	v_cvt_pk_bf16_f32 v62, v56, v57
	v_cvt_pk_bf16_f32 v63, v58, v59
	buffer_store_dwordx4 v[60:63], v229, s[16:19], s34 offen sc1
	v_pk_mul_f32 v[52:53], v[52:53], v[210:211] op_sel:[0,0] op_sel_hi:[1,0]
	v_pk_mul_f32 v[54:55], v[54:55], v[210:211] op_sel:[0,0] op_sel_hi:[1,0]
	v_pk_mul_f32 v[48:49], v[48:49], v[210:211] op_sel:[0,0] op_sel_hi:[1,0]
	v_pk_mul_f32 v[50:51], v[50:51], v[210:211] op_sel:[0,0] op_sel_hi:[1,0]
	v_cvt_pk_bf16_f32 v52, v52, v53
	v_cvt_pk_bf16_f32 v53, v54, v55
	v_cvt_pk_bf16_f32 v54, v48, v49
	v_cvt_pk_bf16_f32 v55, v50, v51
	buffer_store_dwordx4 v[52:55], v229, s[16:19], s34 offen offset:256 sc1
	s_waitcnt lgkmcnt(0)
	v_max3_f32 v227, v154, v156, v158
	v_max_f32_e32 v227, v227, v160
	v_sub_f32_e32 v154, v154, v227
	v_sub_f32_e32 v156, v156, v227
	v_sub_f32_e32 v158, v158, v227
	v_sub_f32_e32 v160, v160, v227
	v_sub_f32_e32 v212, v212, v227
	v_exp_f32_e32 v154, v154
	v_exp_f32_e32 v156, v156
	v_exp_f32_e32 v158, v158
	v_exp_f32_e32 v160, v160
	v_exp_f32_e32 v212, v212
	v_mul_f32_e32 v228, v155, v154
	v_mul_f32_e32 v226, v159, v158
	v_fmac_f32_e32 v228, v157, v156
	v_fmac_f32_e32 v226, v161, v160
	v_add_f32_e32 v228, v228, v226
	v_rcp_f32_e32 v228, v228
	s_nop 0
	v_mul_f32_e32 v212, v212, v228
	s_mov_b32 s34, 0x48000
	v_pk_mul_f32 v[44:45], v[44:45], v[212:213] op_sel:[0,0] op_sel_hi:[1,0]
	v_pk_mul_f32 v[46:47], v[46:47], v[212:213] op_sel:[0,0] op_sel_hi:[1,0]
	v_pk_mul_f32 v[40:41], v[40:41], v[212:213] op_sel:[0,0] op_sel_hi:[1,0]
	v_pk_mul_f32 v[42:43], v[42:43], v[212:213] op_sel:[0,0] op_sel_hi:[1,0]
	v_cvt_pk_bf16_f32 v44, v44, v45
	v_cvt_pk_bf16_f32 v45, v46, v47
	v_cvt_pk_bf16_f32 v46, v40, v41
	v_cvt_pk_bf16_f32 v47, v42, v43
	buffer_store_dwordx4 v[44:47], v229, s[16:19], s34 offen sc1
	v_pk_mul_f32 v[36:37], v[36:37], v[212:213] op_sel:[0,0] op_sel_hi:[1,0]
	v_pk_mul_f32 v[38:39], v[38:39], v[212:213] op_sel:[0,0] op_sel_hi:[1,0]
	v_pk_mul_f32 v[32:33], v[32:33], v[212:213] op_sel:[0,0] op_sel_hi:[1,0]
	v_pk_mul_f32 v[34:35], v[34:35], v[212:213] op_sel:[0,0] op_sel_hi:[1,0]
	v_cvt_pk_bf16_f32 v36, v36, v37
	v_cvt_pk_bf16_f32 v37, v38, v39
	v_cvt_pk_bf16_f32 v38, v32, v33
	v_cvt_pk_bf16_f32 v39, v34, v35
	buffer_store_dwordx4 v[36:39], v229, s[16:19], s34 offen offset:256 sc1
	ds_bpermute_b32 v249, v198, v215
	ds_bpermute_b32 v250, v198, v217
	s_waitcnt lgkmcnt(1)
	v_add_f32_e32 v215, v215, v249
	s_waitcnt lgkmcnt(0)
	v_add_f32_e32 v217, v217, v250
	ds_bpermute_b32 v249, v199, v215
	ds_bpermute_b32 v250, v199, v217
	s_waitcnt lgkmcnt(1)
	v_add_f32_e32 v215, v215, v249
	s_waitcnt lgkmcnt(0)
	v_add_f32_e32 v217, v217, v250
	s_mov_b64 vcc, exec
	s_and_b64 exec, exec, s[0:1]
	ds_write_b64 v180, v[214:215]
	ds_write_b64 v181, v[216:217]
	s_mov_b64 exec, vcc
	s_waitcnt lgkmcnt(0)
	s_barrier
	ds_read_b128 v[146:149], v168 offset:5120
	ds_read_b128 v[150:153], v168 offset:5136
	ds_read_b128 v[154:157], v168 offset:5632
	ds_read_b128 v[158:161], v168 offset:5648
	s_waitcnt lgkmcnt(2)
	v_max3_f32 v227, v146, v148, v150
	v_max_f32_e32 v227, v227, v152
	v_sub_f32_e32 v146, v146, v227
	v_sub_f32_e32 v148, v148, v227
	v_sub_f32_e32 v150, v150, v227
	v_sub_f32_e32 v152, v152, v227
	v_sub_f32_e32 v214, v214, v227
	v_exp_f32_e32 v146, v146
	v_exp_f32_e32 v148, v148
	v_exp_f32_e32 v150, v150
	v_exp_f32_e32 v152, v152
	v_exp_f32_e32 v214, v214
	v_mul_f32_e32 v228, v147, v146
	v_mul_f32_e32 v226, v151, v150
	v_fmac_f32_e32 v228, v149, v148
	v_fmac_f32_e32 v226, v153, v152
	v_add_f32_e32 v228, v228, v226
	v_rcp_f32_e32 v228, v228
	s_nop 0
	v_mul_f32_e32 v214, v214, v228
	s_mov_b32 s34, 0x50000
	v_pk_mul_f32 v[28:29], v[28:29], v[214:215] op_sel:[0,0] op_sel_hi:[1,0]
	v_pk_mul_f32 v[30:31], v[30:31], v[214:215] op_sel:[0,0] op_sel_hi:[1,0]
	v_pk_mul_f32 v[24:25], v[24:25], v[214:215] op_sel:[0,0] op_sel_hi:[1,0]
	v_pk_mul_f32 v[26:27], v[26:27], v[214:215] op_sel:[0,0] op_sel_hi:[1,0]
	v_cvt_pk_bf16_f32 v28, v28, v29
	v_cvt_pk_bf16_f32 v29, v30, v31
	v_cvt_pk_bf16_f32 v30, v24, v25
	v_cvt_pk_bf16_f32 v31, v26, v27
	buffer_store_dwordx4 v[28:31], v229, s[16:19], s34 offen sc1
	v_pk_mul_f32 v[20:21], v[20:21], v[214:215] op_sel:[0,0] op_sel_hi:[1,0]
	v_pk_mul_f32 v[22:23], v[22:23], v[214:215] op_sel:[0,0] op_sel_hi:[1,0]
	v_pk_mul_f32 v[16:17], v[16:17], v[214:215] op_sel:[0,0] op_sel_hi:[1,0]
	v_pk_mul_f32 v[18:19], v[18:19], v[214:215] op_sel:[0,0] op_sel_hi:[1,0]
	v_cvt_pk_bf16_f32 v20, v20, v21
	v_cvt_pk_bf16_f32 v21, v22, v23
	v_cvt_pk_bf16_f32 v22, v16, v17
	v_cvt_pk_bf16_f32 v23, v18, v19
	buffer_store_dwordx4 v[20:23], v229, s[16:19], s34 offen offset:256 sc1
	s_waitcnt lgkmcnt(0)
	v_max3_f32 v227, v154, v156, v158
	v_max_f32_e32 v227, v227, v160
	v_sub_f32_e32 v154, v154, v227
	v_sub_f32_e32 v156, v156, v227
	v_sub_f32_e32 v158, v158, v227
	v_sub_f32_e32 v160, v160, v227
	v_sub_f32_e32 v216, v216, v227
	v_exp_f32_e32 v154, v154
	v_exp_f32_e32 v156, v156
	v_exp_f32_e32 v158, v158
	v_exp_f32_e32 v160, v160
	v_exp_f32_e32 v216, v216
	v_mul_f32_e32 v228, v155, v154
	v_mul_f32_e32 v226, v159, v158
	v_fmac_f32_e32 v228, v157, v156
	v_fmac_f32_e32 v226, v161, v160
	v_add_f32_e32 v228, v228, v226
	v_rcp_f32_e32 v228, v228
	s_nop 0
	v_mul_f32_e32 v216, v216, v228
	s_mov_b32 s34, 0x58000
	v_pk_mul_f32 v[12:13], v[12:13], v[216:217] op_sel:[0,0] op_sel_hi:[1,0]
	v_pk_mul_f32 v[14:15], v[14:15], v[216:217] op_sel:[0,0] op_sel_hi:[1,0]
	v_pk_mul_f32 v[8:9], v[8:9], v[216:217] op_sel:[0,0] op_sel_hi:[1,0]
	v_pk_mul_f32 v[10:11], v[10:11], v[216:217] op_sel:[0,0] op_sel_hi:[1,0]
	v_cvt_pk_bf16_f32 v12, v12, v13
	v_cvt_pk_bf16_f32 v13, v14, v15
	v_cvt_pk_bf16_f32 v14, v8, v9
	v_cvt_pk_bf16_f32 v15, v10, v11
	buffer_store_dwordx4 v[12:15], v229, s[16:19], s34 offen sc1
	v_pk_mul_f32 v[4:5], v[4:5], v[216:217] op_sel:[0,0] op_sel_hi:[1,0]
	v_pk_mul_f32 v[6:7], v[6:7], v[216:217] op_sel:[0,0] op_sel_hi:[1,0]
	v_pk_mul_f32 v[0:1], v[0:1], v[216:217] op_sel:[0,0] op_sel_hi:[1,0]
	v_pk_mul_f32 v[2:3], v[2:3], v[216:217] op_sel:[0,0] op_sel_hi:[1,0]
	v_cvt_pk_bf16_f32 v4, v4, v5
	v_cvt_pk_bf16_f32 v5, v6, v7
	v_cvt_pk_bf16_f32 v6, v0, v1
	v_cvt_pk_bf16_f32 v7, v2, v3
	buffer_store_dwordx4 v[4:7], v229, s[16:19], s34 offen offset:256 sc1
	s_waitcnt lgkmcnt(0)
	s_andn2_b64 vcc, exec, s[4:5]
	s_mov_b64 s[4:5], -1
	s_cbranch_vccnz .LBB0_506
	s_andn2_b64 vcc, exec, s[6:7]
	s_cbranch_vccnz .LBB0_505
	s_barrier
	s_branch .LBB0_505

.LBB0_680:
	s_mov_b64 s[12:13], 0x80
	s_and_b32 s6, s1, 3
	s_add_i32 m0, s23, 0x18000
	v_lshl_add_u64 v[6:7], v[6:7], 0, s[12:13]
	s_and_b32 s5, s75, 0xffff
	s_ashr_i32 s44, s97, 31
	s_lshl_b32 s16, s4, 6
	s_lshl_b32 s15, s4, 13
	s_lshl_b32 s17, s6, 12
	s_waitcnt vmcnt(2)
	s_barrier
	global_load_lds_dwordx4 v[6:7], off
	v_lshl_add_u64 v[4:5], v[4:5], 0, s[12:13]
	s_add_i32 m0, s23, 0x1a000
	s_add_i32 s45, s23, 0x8000
	s_add_i32 s46, s23, 0xa000
	global_load_lds_dwordx4 v[4:5], off
	v_lshl_add_u64 v[0:1], v[0:1], 0, s[12:13]
	s_mov_b32 m0, s45
	s_add_u32 s6, s30, 0x40080
	global_load_lds_dwordx4 v[0:1], off
	v_lshl_add_u64 v[0:1], v[2:3], 0, s[12:13]
	s_mov_b32 m0, s46
	s_addc_u32 s7, s31, 0
	global_load_lds_dwordx4 v[0:1], off
	s_add_i32 m0, s23, 0x1c000
	v_lshl_add_u64 v[0:1], s[6:7], 0, v[132:133]
	global_load_lds_dwordx4 v[0:1], off
	v_lshl_add_u64 v[0:1], s[6:7], 0, v[128:129]
	s_add_i32 m0, s23, 0x1e000
	v_and_b32_e32 v2, 15, v10
	global_load_lds_dwordx4 v[0:1], off
	v_and_b32_e32 v0, 48, v10
	v_lshlrev_b32_e32 v3, 2, v10
	v_lshl_or_b32 v1, v2, 6, v0
	v_and_b32_e32 v3, 32, v3
	s_cmpk_lt_u32 s14, 0x100
	s_sext_i32_i8 s50, s0
	v_bitop3_b32 v4, v1, s15, v3 bitop3:0xde
	s_cselect_b64 s[14:15], -1, 0
	s_lshl_b32 s0, s1, 7
	v_bitop3_b32 v151, v1, s17, v3 bitop3:0xde
	v_mov_b32_e32 v1, v133
	s_and_b32 s47, s0, 0x100
	s_lshl_b32 s0, s1, 6
	v_lshl_add_u64 v[136:137], s[2:3], 0, v[0:1]
	v_and_or_b32 v153, s0, 64, v0
	v_mov_b32_e32 v0, 0xcf
	v_bitop3_b32 v155, s16, v0, v2 bitop3:0xc8
	v_lshlrev_b32_e32 v0, 14, v13
	v_and_b32_e32 v0, 0xffff8000, v0
	v_lshl_add_u32 v0, v12, 11, v0
	v_and_b32_e32 v1, 1, v13
	v_lshl_or_b32 v0, v1, 6, v0
	v_lshl_add_u32 v138, v14, 1, v0
	v_lshlrev_b32_e32 v0, 14, v8
	v_and_b32_e32 v0, 0xffff8000, v0
	v_lshl_add_u32 v0, v9, 11, v0
	v_and_b32_e32 v1, 1, v8
	s_waitcnt vmcnt(6)
	v_lshl_or_b32 v0, v1, 6, v0
	v_lshl_add_u32 v140, v11, 1, v0
	s_add_i32 s48, 0, 0x10000
	s_add_i32 s49, 0, 0x14000
	v_mbcnt_lo_u32_b32 v0, -1, 0
	s_mov_b32 s7, 0x20000
	s_mov_b32 s6, 0x7ffffff0
	s_mov_b32 s4, s74
	v_or_b32_e32 v147, s16, v2
	v_mov_b32_e32 v139, v133
	v_mov_b32_e32 v141, v133
	v_mov_b64_e32 v[142:143], 0x800
	v_mov_b64_e32 v[144:145], 0x7ff
	v_add_u32_e32 v157, s48, v151
	v_add_u32_e32 v158, s49, v151
	v_add_u32_e32 v159, 0, v4
	v_mbcnt_hi_u32_b32 v160, -1, v0
	v_mov_b32_e32 v161, 0x358637bd
	s_mov_b64 s[18:19], s[28:29]
	s_mov_b64 s[20:21], s[30:31]
	v_mov_b32_e32 v246, -1
	s_barrier
	s_branch .LBB0_683

.LBB0_693:
	v_readfirstlane_b32 s3, v246
	s_lshl_b32 s17, s22, 14
	s_cmp_eq_u32 s3, s22
	s_cbranch_scc1 .Lup_rs_ok
	v_lshl_add_u32 v148, s22, 8, v147
	v_lshlrev_b32_e32 v148, 6, v148
	v_add_co_u32_e32 v194, vcc, v136, v148
	s_nop 1
	v_addc_co_u32_e32 v195, vcc, 0, v137, vcc
	v_add_co_u32_e32 v250, vcc, 0x2000, v194
	s_nop 1
	v_addc_co_u32_e32 v251, vcc, 0, v195, vcc
	global_load_dwordx4 v[162:165], v[194:195], off
	global_load_dwordx4 v[166:169], v[194:195], off offset:1024
	global_load_dwordx4 v[170:173], v[194:195], off offset:2048
	global_load_dwordx4 v[174:177], v[194:195], off offset:3072
	global_load_dwordx4 v[178:181], v[250:251], off
	global_load_dwordx4 v[182:185], v[250:251], off offset:1024
	global_load_dwordx4 v[186:189], v[250:251], off offset:2048
	global_load_dwordx4 v[190:193], v[250:251], off offset:3072
	v_xor_b32_e32 v146, 16, v160
	v_xor_b32_e32 v149, 32, v160
	v_lshlrev_b32_e32 v146, 2, v146
	v_lshlrev_b32_e32 v149, 2, v149
	v_mov_b32_e32 v246, s22
	s_waitcnt vmcnt(7)
	v_add_f32_e32 v162, v162, v163
	v_add_f32_e32 v164, v164, v165
	v_add_f32_e32 v238, v162, v164
	s_waitcnt vmcnt(6)
	v_add_f32_e32 v166, v166, v167
	v_add_f32_e32 v168, v168, v169
	v_add_f32_e32 v239, v166, v168
	s_waitcnt vmcnt(5)
	v_add_f32_e32 v170, v170, v171
	v_add_f32_e32 v172, v172, v173
	v_add_f32_e32 v240, v170, v172
	s_waitcnt vmcnt(4)
	v_add_f32_e32 v174, v174, v175
	v_add_f32_e32 v176, v176, v177
	v_add_f32_e32 v241, v174, v176
	s_waitcnt vmcnt(3)
	v_add_f32_e32 v178, v178, v179
	v_add_f32_e32 v180, v180, v181
	v_add_f32_e32 v242, v178, v180
	s_waitcnt vmcnt(2)
	v_add_f32_e32 v182, v182, v183
	v_add_f32_e32 v184, v184, v185
	v_add_f32_e32 v243, v182, v184
	s_waitcnt vmcnt(1)
	v_add_f32_e32 v186, v186, v187
	v_add_f32_e32 v188, v188, v189
	v_add_f32_e32 v244, v186, v188
	s_waitcnt vmcnt(0)
	v_add_f32_e32 v190, v190, v191
	v_add_f32_e32 v192, v192, v193
	v_add_f32_e32 v245, v190, v192
	ds_bpermute_b32 v162, v146, v238
	ds_bpermute_b32 v163, v146, v239
	ds_bpermute_b32 v164, v146, v240
	ds_bpermute_b32 v165, v146, v241
	ds_bpermute_b32 v166, v146, v242
	ds_bpermute_b32 v167, v146, v243
	ds_bpermute_b32 v168, v146, v244
	ds_bpermute_b32 v169, v146, v245
	s_waitcnt lgkmcnt(7)
	v_add_f32_e32 v238, v238, v162
	s_waitcnt lgkmcnt(6)
	v_add_f32_e32 v239, v239, v163
	s_waitcnt lgkmcnt(5)
	v_add_f32_e32 v240, v240, v164
	s_waitcnt lgkmcnt(4)
	v_add_f32_e32 v241, v241, v165
	s_waitcnt lgkmcnt(3)
	v_add_f32_e32 v242, v242, v166
	s_waitcnt lgkmcnt(2)
	v_add_f32_e32 v243, v243, v167
	s_waitcnt lgkmcnt(1)
	v_add_f32_e32 v244, v244, v168
	s_waitcnt lgkmcnt(0)
	v_add_f32_e32 v245, v245, v169
	ds_bpermute_b32 v162, v149, v238
	ds_bpermute_b32 v163, v149, v239
	ds_bpermute_b32 v164, v149, v240
	ds_bpermute_b32 v165, v149, v241
	ds_bpermute_b32 v166, v149, v242
	ds_bpermute_b32 v167, v149, v243
	ds_bpermute_b32 v168, v149, v244
	ds_bpermute_b32 v169, v149, v245
	s_waitcnt lgkmcnt(7)
	v_add_f32_e32 v238, v238, v162
	s_waitcnt lgkmcnt(6)
	v_add_f32_e32 v239, v239, v163
	s_waitcnt lgkmcnt(5)
	v_add_f32_e32 v240, v240, v164
	s_waitcnt lgkmcnt(4)
	v_add_f32_e32 v241, v241, v165
	s_waitcnt lgkmcnt(3)
	v_add_f32_e32 v242, v242, v166
	s_waitcnt lgkmcnt(2)
	v_add_f32_e32 v243, v243, v167
	s_waitcnt lgkmcnt(1)
	v_add_f32_e32 v244, v244, v168
	s_waitcnt lgkmcnt(0)
	v_add_f32_e32 v245, v245, v169
	v_fmamk_f32 v238, v238, 0x3a800000, v161
	v_fmamk_f32 v239, v239, 0x3a800000, v161
	v_fmamk_f32 v240, v240, 0x3a800000, v161
	v_fmamk_f32 v241, v241, 0x3a800000, v161
	v_fmamk_f32 v242, v242, 0x3a800000, v161
	v_fmamk_f32 v243, v243, 0x3a800000, v161
	v_fmamk_f32 v244, v244, 0x3a800000, v161
	v_fmamk_f32 v245, v245, 0x3a800000, v161
	v_rsq_f32_e32 v238, v238
	v_rsq_f32_e32 v239, v239
	v_rsq_f32_e32 v240, v240
	v_rsq_f32_e32 v241, v241
	v_rsq_f32_e32 v242, v242
	v_rsq_f32_e32 v243, v243
	v_rsq_f32_e32 v244, v244
	v_rsq_f32_e32 v245, v245
.Lup_rs_ok:
	s_lshl_b32 s3, s50, 10
	s_add_i32 s17, s17, s3
	s_or_b32 s3, s17, s47
	v_or_b32_e32 v150, s3, v155
	v_lshl_or_b32 v150, v150, 7, v153
	v_pk_mul_f32 v[124:125], v[124:125], v[238:239] op_sel:[0,0] op_sel_hi:[1,0]
	v_pk_mul_f32 v[126:127], v[126:127], v[238:239] op_sel:[0,0] op_sel_hi:[1,0]
	v_pk_mul_f32 v[120:121], v[120:121], v[238:239] op_sel:[0,0] op_sel_hi:[1,0]
	v_pk_mul_f32 v[122:123], v[122:123], v[238:239] op_sel:[0,0] op_sel_hi:[1,0]
	v_max_f32_e32 v162, 0, v124
	v_max_f32_e32 v163, 0, v125
	v_max_f32_e32 v164, 0, v126
	v_max_f32_e32 v165, 0, v127
	v_max_f32_e32 v166, 0, v120
	v_max_f32_e32 v167, 0, v121
	v_max_f32_e32 v168, 0, v122
	v_max_f32_e32 v169, 0, v123
	v_pk_mul_f32 v[162:163], v[162:163], v[162:163]
	v_pk_mul_f32 v[164:165], v[164:165], v[164:165]
	v_pk_mul_f32 v[166:167], v[166:167], v[166:167]
	v_pk_mul_f32 v[168:169], v[168:169], v[168:169]
	v_cvt_pk_bf16_f32 v124, v162, v163
	v_cvt_pk_bf16_f32 v125, v164, v165
	v_cvt_pk_bf16_f32 v126, v166, v167
	v_cvt_pk_bf16_f32 v127, v168, v169
	s_mov_b32 s17, 0x0
	buffer_store_dwordx4 v[124:127], v150, s[4:7], s17 offen nt sc1
	v_pk_mul_f32 v[116:117], v[116:117], v[238:239] op_sel:[0,0] op_sel_hi:[1,0]
	v_pk_mul_f32 v[118:119], v[118:119], v[238:239] op_sel:[0,0] op_sel_hi:[1,0]
	v_pk_mul_f32 v[112:113], v[112:113], v[238:239] op_sel:[0,0] op_sel_hi:[1,0]
	v_pk_mul_f32 v[114:115], v[114:115], v[238:239] op_sel:[0,0] op_sel_hi:[1,0]
	v_max_f32_e32 v170, 0, v116
	v_max_f32_e32 v171, 0, v117
	v_max_f32_e32 v172, 0, v118
	v_max_f32_e32 v173, 0, v119
	v_max_f32_e32 v174, 0, v112
	v_max_f32_e32 v175, 0, v113
	v_max_f32_e32 v176, 0, v114
	v_max_f32_e32 v177, 0, v115
	v_pk_mul_f32 v[170:171], v[170:171], v[170:171]
	v_pk_mul_f32 v[172:173], v[172:173], v[172:173]
	v_pk_mul_f32 v[174:175], v[174:175], v[174:175]
	v_pk_mul_f32 v[176:177], v[176:177], v[176:177]
	v_cvt_pk_bf16_f32 v116, v170, v171
	v_cvt_pk_bf16_f32 v117, v172, v173
	v_cvt_pk_bf16_f32 v118, v174, v175
	v_cvt_pk_bf16_f32 v119, v176, v177
	s_mov_b32 s17, 0x10000
	buffer_store_dwordx4 v[116:119], v150, s[4:7], s17 offen nt sc1
	v_pk_mul_f32 v[108:109], v[108:109], v[238:239] op_sel:[0,1] op_sel_hi:[1,1]
	v_pk_mul_f32 v[110:111], v[110:111], v[238:239] op_sel:[0,1] op_sel_hi:[1,1]
	v_pk_mul_f32 v[104:105], v[104:105], v[238:239] op_sel:[0,1] op_sel_hi:[1,1]
	v_pk_mul_f32 v[106:107], v[106:107], v[238:239] op_sel:[0,1] op_sel_hi:[1,1]
	v_max_f32_e32 v162, 0, v108
	v_max_f32_e32 v163, 0, v109
	v_max_f32_e32 v164, 0, v110
	v_max_f32_e32 v165, 0, v111
	v_max_f32_e32 v166, 0, v104
	v_max_f32_e32 v167, 0, v105
	v_max_f32_e32 v168, 0, v106
	v_max_f32_e32 v169, 0, v107
	v_pk_mul_f32 v[162:163], v[162:163], v[162:163]
	v_pk_mul_f32 v[164:165], v[164:165], v[164:165]
	v_pk_mul_f32 v[166:167], v[166:167], v[166:167]
	v_pk_mul_f32 v[168:169], v[168:169], v[168:169]
	v_cvt_pk_bf16_f32 v108, v162, v163
	v_cvt_pk_bf16_f32 v109, v164, v165
	v_cvt_pk_bf16_f32 v110, v166, v167
	v_cvt_pk_bf16_f32 v111, v168, v169
	s_mov_b32 s17, 0x0
	buffer_store_dwordx4 v[108:111], v150, s[4:7], s17 offen offset:2048 nt sc1
	v_pk_mul_f32 v[100:101], v[100:101], v[238:239] op_sel:[0,1] op_sel_hi:[1,1]
	v_pk_mul_f32 v[102:103], v[102:103], v[238:239] op_sel:[0,1] op_sel_hi:[1,1]
	v_pk_mul_f32 v[96:97], v[96:97], v[238:239] op_sel:[0,1] op_sel_hi:[1,1]
	v_pk_mul_f32 v[98:99], v[98:99], v[238:239] op_sel:[0,1] op_sel_hi:[1,1]
	v_max_f32_e32 v170, 0, v100
	v_max_f32_e32 v171, 0, v101
	v_max_f32_e32 v172, 0, v102
	v_max_f32_e32 v173, 0, v103
	v_max_f32_e32 v174, 0, v96
	v_max_f32_e32 v175, 0, v97
	v_max_f32_e32 v176, 0, v98
	v_max_f32_e32 v177, 0, v99
	v_pk_mul_f32 v[170:171], v[170:171], v[170:171]
	v_pk_mul_f32 v[172:173], v[172:173], v[172:173]
	v_pk_mul_f32 v[174:175], v[174:175], v[174:175]
	v_pk_mul_f32 v[176:177], v[176:177], v[176:177]
	v_cvt_pk_bf16_f32 v100, v170, v171
	v_cvt_pk_bf16_f32 v101, v172, v173
	v_cvt_pk_bf16_f32 v102, v174, v175
	v_cvt_pk_bf16_f32 v103, v176, v177
	s_mov_b32 s17, 0x10000
	buffer_store_dwordx4 v[100:103], v150, s[4:7], s17 offen offset:2048 nt sc1
	v_pk_mul_f32 v[92:93], v[92:93], v[240:241] op_sel:[0,0] op_sel_hi:[1,0]
	v_pk_mul_f32 v[94:95], v[94:95], v[240:241] op_sel:[0,0] op_sel_hi:[1,0]
	v_pk_mul_f32 v[88:89], v[88:89], v[240:241] op_sel:[0,0] op_sel_hi:[1,0]
	v_pk_mul_f32 v[90:91], v[90:91], v[240:241] op_sel:[0,0] op_sel_hi:[1,0]
	v_max_f32_e32 v162, 0, v92
	v_max_f32_e32 v163, 0, v93
	v_max_f32_e32 v164, 0, v94
	v_max_f32_e32 v165, 0, v95
	v_max_f32_e32 v166, 0, v88
	v_max_f32_e32 v167, 0, v89
	v_max_f32_e32 v168, 0, v90
	v_max_f32_e32 v169, 0, v91
	v_pk_mul_f32 v[162:163], v[162:163], v[162:163]
	v_pk_mul_f32 v[164:165], v[164:165], v[164:165]
	v_pk_mul_f32 v[166:167], v[166:167], v[166:167]
	v_pk_mul_f32 v[168:169], v[168:169], v[168:169]
	v_cvt_pk_bf16_f32 v92, v162, v163
	v_cvt_pk_bf16_f32 v93, v164, v165
	v_cvt_pk_bf16_f32 v94, v166, v167
	v_cvt_pk_bf16_f32 v95, v168, v169
	s_mov_b32 s17, 0x1000
	buffer_store_dwordx4 v[92:95], v150, s[4:7], s17 offen nt sc1
	v_pk_mul_f32 v[84:85], v[84:85], v[240:241] op_sel:[0,0] op_sel_hi:[1,0]
	v_pk_mul_f32 v[86:87], v[86:87], v[240:241] op_sel:[0,0] op_sel_hi:[1,0]
	v_pk_mul_f32 v[80:81], v[80:81], v[240:241] op_sel:[0,0] op_sel_hi:[1,0]
	v_pk_mul_f32 v[82:83], v[82:83], v[240:241] op_sel:[0,0] op_sel_hi:[1,0]
	v_max_f32_e32 v170, 0, v84
	v_max_f32_e32 v171, 0, v85
	v_max_f32_e32 v172, 0, v86
	v_max_f32_e32 v173, 0, v87
	v_max_f32_e32 v174, 0, v80
	v_max_f32_e32 v175, 0, v81
	v_max_f32_e32 v176, 0, v82
	v_max_f32_e32 v177, 0, v83
	v_pk_mul_f32 v[170:171], v[170:171], v[170:171]
	v_pk_mul_f32 v[172:173], v[172:173], v[172:173]
	v_pk_mul_f32 v[174:175], v[174:175], v[174:175]
	v_pk_mul_f32 v[176:177], v[176:177], v[176:177]
	v_cvt_pk_bf16_f32 v84, v170, v171
	v_cvt_pk_bf16_f32 v85, v172, v173
	v_cvt_pk_bf16_f32 v86, v174, v175
	v_cvt_pk_bf16_f32 v87, v176, v177
	s_mov_b32 s17, 0x11000
	buffer_store_dwordx4 v[84:87], v150, s[4:7], s17 offen nt sc1
	v_pk_mul_f32 v[76:77], v[76:77], v[240:241] op_sel:[0,1] op_sel_hi:[1,1]
	v_pk_mul_f32 v[78:79], v[78:79], v[240:241] op_sel:[0,1] op_sel_hi:[1,1]
	v_pk_mul_f32 v[72:73], v[72:73], v[240:241] op_sel:[0,1] op_sel_hi:[1,1]
	v_pk_mul_f32 v[74:75], v[74:75], v[240:241] op_sel:[0,1] op_sel_hi:[1,1]
	v_max_f32_e32 v162, 0, v76
	v_max_f32_e32 v163, 0, v77
	v_max_f32_e32 v164, 0, v78
	v_max_f32_e32 v165, 0, v79
	v_max_f32_e32 v166, 0, v72
	v_max_f32_e32 v167, 0, v73
	v_max_f32_e32 v168, 0, v74
	v_max_f32_e32 v169, 0, v75
	v_pk_mul_f32 v[162:163], v[162:163], v[162:163]
	v_pk_mul_f32 v[164:165], v[164:165], v[164:165]
	v_pk_mul_f32 v[166:167], v[166:167], v[166:167]
	v_pk_mul_f32 v[168:169], v[168:169], v[168:169]
	v_cvt_pk_bf16_f32 v76, v162, v163
	v_cvt_pk_bf16_f32 v77, v164, v165
	v_cvt_pk_bf16_f32 v78, v166, v167
	v_cvt_pk_bf16_f32 v79, v168, v169
	s_mov_b32 s17, 0x1000
	buffer_store_dwordx4 v[76:79], v150, s[4:7], s17 offen offset:2048 nt sc1
	v_pk_mul_f32 v[68:69], v[68:69], v[240:241] op_sel:[0,1] op_sel_hi:[1,1]
	v_pk_mul_f32 v[70:71], v[70:71], v[240:241] op_sel:[0,1] op_sel_hi:[1,1]
	v_pk_mul_f32 v[64:65], v[64:65], v[240:241] op_sel:[0,1] op_sel_hi:[1,1]
	v_pk_mul_f32 v[66:67], v[66:67], v[240:241] op_sel:[0,1] op_sel_hi:[1,1]
	v_max_f32_e32 v170, 0, v68
	v_max_f32_e32 v171, 0, v69
	v_max_f32_e32 v172, 0, v70
	v_max_f32_e32 v173, 0, v71
	v_max_f32_e32 v174, 0, v64
	v_max_f32_e32 v175, 0, v65
	v_max_f32_e32 v176, 0, v66
	v_max_f32_e32 v177, 0, v67
	v_pk_mul_f32 v[170:171], v[170:171], v[170:171]
	v_pk_mul_f32 v[172:173], v[172:173], v[172:173]
	v_pk_mul_f32 v[174:175], v[174:175], v[174:175]
	v_pk_mul_f32 v[176:177], v[176:177], v[176:177]
	v_cvt_pk_bf16_f32 v68, v170, v171
	v_cvt_pk_bf16_f32 v69, v172, v173
	v_cvt_pk_bf16_f32 v70, v174, v175
	v_cvt_pk_bf16_f32 v71, v176, v177
	s_mov_b32 s17, 0x11000
	buffer_store_dwordx4 v[68:71], v150, s[4:7], s17 offen offset:2048 nt sc1
	v_pk_mul_f32 v[60:61], v[60:61], v[242:243] op_sel:[0,0] op_sel_hi:[1,0]
	v_pk_mul_f32 v[62:63], v[62:63], v[242:243] op_sel:[0,0] op_sel_hi:[1,0]
	v_pk_mul_f32 v[56:57], v[56:57], v[242:243] op_sel:[0,0] op_sel_hi:[1,0]
	v_pk_mul_f32 v[58:59], v[58:59], v[242:243] op_sel:[0,0] op_sel_hi:[1,0]
	v_max_f32_e32 v162, 0, v60
	v_max_f32_e32 v163, 0, v61
	v_max_f32_e32 v164, 0, v62
	v_max_f32_e32 v165, 0, v63
	v_max_f32_e32 v166, 0, v56
	v_max_f32_e32 v167, 0, v57
	v_max_f32_e32 v168, 0, v58
	v_max_f32_e32 v169, 0, v59
	v_pk_mul_f32 v[162:163], v[162:163], v[162:163]
	v_pk_mul_f32 v[164:165], v[164:165], v[164:165]
	v_pk_mul_f32 v[166:167], v[166:167], v[166:167]
	v_pk_mul_f32 v[168:169], v[168:169], v[168:169]
	v_cvt_pk_bf16_f32 v60, v162, v163
	v_cvt_pk_bf16_f32 v61, v164, v165
	v_cvt_pk_bf16_f32 v62, v166, v167
	v_cvt_pk_bf16_f32 v63, v168, v169
	s_mov_b32 s17, 0x4000
	buffer_store_dwordx4 v[60:63], v150, s[4:7], s17 offen nt sc1
	v_pk_mul_f32 v[52:53], v[52:53], v[242:243] op_sel:[0,0] op_sel_hi:[1,0]
	v_pk_mul_f32 v[54:55], v[54:55], v[242:243] op_sel:[0,0] op_sel_hi:[1,0]
	v_pk_mul_f32 v[48:49], v[48:49], v[242:243] op_sel:[0,0] op_sel_hi:[1,0]
	v_pk_mul_f32 v[50:51], v[50:51], v[242:243] op_sel:[0,0] op_sel_hi:[1,0]
	v_max_f32_e32 v170, 0, v52
	v_max_f32_e32 v171, 0, v53
	v_max_f32_e32 v172, 0, v54
	v_max_f32_e32 v173, 0, v55
	v_max_f32_e32 v174, 0, v48
	v_max_f32_e32 v175, 0, v49
	v_max_f32_e32 v176, 0, v50
	v_max_f32_e32 v177, 0, v51
	v_pk_mul_f32 v[170:171], v[170:171], v[170:171]
	v_pk_mul_f32 v[172:173], v[172:173], v[172:173]
	v_pk_mul_f32 v[174:175], v[174:175], v[174:175]
	v_pk_mul_f32 v[176:177], v[176:177], v[176:177]
	v_cvt_pk_bf16_f32 v52, v170, v171
	v_cvt_pk_bf16_f32 v53, v172, v173
	v_cvt_pk_bf16_f32 v54, v174, v175
	v_cvt_pk_bf16_f32 v55, v176, v177
	s_mov_b32 s17, 0x14000
	buffer_store_dwordx4 v[52:55], v150, s[4:7], s17 offen nt sc1
	v_pk_mul_f32 v[44:45], v[44:45], v[242:243] op_sel:[0,1] op_sel_hi:[1,1]
	v_pk_mul_f32 v[46:47], v[46:47], v[242:243] op_sel:[0,1] op_sel_hi:[1,1]
	v_pk_mul_f32 v[40:41], v[40:41], v[242:243] op_sel:[0,1] op_sel_hi:[1,1]
	v_pk_mul_f32 v[42:43], v[42:43], v[242:243] op_sel:[0,1] op_sel_hi:[1,1]
	v_max_f32_e32 v162, 0, v44
	v_max_f32_e32 v163, 0, v45
	v_max_f32_e32 v164, 0, v46
	v_max_f32_e32 v165, 0, v47
	v_max_f32_e32 v166, 0, v40
	v_max_f32_e32 v167, 0, v41
	v_max_f32_e32 v168, 0, v42
	v_max_f32_e32 v169, 0, v43
	v_pk_mul_f32 v[162:163], v[162:163], v[162:163]
	v_pk_mul_f32 v[164:165], v[164:165], v[164:165]
	v_pk_mul_f32 v[166:167], v[166:167], v[166:167]
	v_pk_mul_f32 v[168:169], v[168:169], v[168:169]
	v_cvt_pk_bf16_f32 v44, v162, v163
	v_cvt_pk_bf16_f32 v45, v164, v165
	v_cvt_pk_bf16_f32 v46, v166, v167
	v_cvt_pk_bf16_f32 v47, v168, v169
	s_mov_b32 s17, 0x4000
	buffer_store_dwordx4 v[44:47], v150, s[4:7], s17 offen offset:2048 nt sc1
	v_pk_mul_f32 v[36:37], v[36:37], v[242:243] op_sel:[0,1] op_sel_hi:[1,1]
	v_pk_mul_f32 v[38:39], v[38:39], v[242:243] op_sel:[0,1] op_sel_hi:[1,1]
	v_pk_mul_f32 v[32:33], v[32:33], v[242:243] op_sel:[0,1] op_sel_hi:[1,1]
	v_pk_mul_f32 v[34:35], v[34:35], v[242:243] op_sel:[0,1] op_sel_hi:[1,1]
	v_max_f32_e32 v170, 0, v36
	v_max_f32_e32 v171, 0, v37
	v_max_f32_e32 v172, 0, v38
	v_max_f32_e32 v173, 0, v39
	v_max_f32_e32 v174, 0, v32
	v_max_f32_e32 v175, 0, v33
	v_max_f32_e32 v176, 0, v34
	v_max_f32_e32 v177, 0, v35
	v_pk_mul_f32 v[170:171], v[170:171], v[170:171]
	v_pk_mul_f32 v[172:173], v[172:173], v[172:173]
	v_pk_mul_f32 v[174:175], v[174:175], v[174:175]
	v_pk_mul_f32 v[176:177], v[176:177], v[176:177]
	v_cvt_pk_bf16_f32 v36, v170, v171
	v_cvt_pk_bf16_f32 v37, v172, v173
	v_cvt_pk_bf16_f32 v38, v174, v175
	v_cvt_pk_bf16_f32 v39, v176, v177
	s_mov_b32 s17, 0x14000
	buffer_store_dwordx4 v[36:39], v150, s[4:7], s17 offen offset:2048 nt sc1
	v_pk_mul_f32 v[28:29], v[28:29], v[244:245] op_sel:[0,0] op_sel_hi:[1,0]
	v_pk_mul_f32 v[30:31], v[30:31], v[244:245] op_sel:[0,0] op_sel_hi:[1,0]
	v_pk_mul_f32 v[24:25], v[24:25], v[244:245] op_sel:[0,0] op_sel_hi:[1,0]
	v_pk_mul_f32 v[26:27], v[26:27], v[244:245] op_sel:[0,0] op_sel_hi:[1,0]
	v_max_f32_e32 v162, 0, v28
	v_max_f32_e32 v163, 0, v29
	v_max_f32_e32 v164, 0, v30
	v_max_f32_e32 v165, 0, v31
	v_max_f32_e32 v166, 0, v24
	v_max_f32_e32 v167, 0, v25
	v_max_f32_e32 v168, 0, v26
	v_max_f32_e32 v169, 0, v27
	v_pk_mul_f32 v[162:163], v[162:163], v[162:163]
	v_pk_mul_f32 v[164:165], v[164:165], v[164:165]
	v_pk_mul_f32 v[166:167], v[166:167], v[166:167]
	v_pk_mul_f32 v[168:169], v[168:169], v[168:169]
	v_cvt_pk_bf16_f32 v28, v162, v163
	v_cvt_pk_bf16_f32 v29, v164, v165
	v_cvt_pk_bf16_f32 v30, v166, v167
	v_cvt_pk_bf16_f32 v31, v168, v169
	s_mov_b32 s17, 0x5000
	buffer_store_dwordx4 v[28:31], v150, s[4:7], s17 offen nt sc1
	v_pk_mul_f32 v[20:21], v[20:21], v[244:245] op_sel:[0,0] op_sel_hi:[1,0]
	v_pk_mul_f32 v[22:23], v[22:23], v[244:245] op_sel:[0,0] op_sel_hi:[1,0]
	v_pk_mul_f32 v[16:17], v[16:17], v[244:245] op_sel:[0,0] op_sel_hi:[1,0]
	v_pk_mul_f32 v[18:19], v[18:19], v[244:245] op_sel:[0,0] op_sel_hi:[1,0]
	v_max_f32_e32 v170, 0, v20
	v_max_f32_e32 v171, 0, v21
	v_max_f32_e32 v172, 0, v22
	v_max_f32_e32 v173, 0, v23
	v_max_f32_e32 v174, 0, v16
	v_max_f32_e32 v175, 0, v17
	v_max_f32_e32 v176, 0, v18
	v_max_f32_e32 v177, 0, v19
	v_pk_mul_f32 v[170:171], v[170:171], v[170:171]
	v_pk_mul_f32 v[172:173], v[172:173], v[172:173]
	v_pk_mul_f32 v[174:175], v[174:175], v[174:175]
	v_pk_mul_f32 v[176:177], v[176:177], v[176:177]
	v_cvt_pk_bf16_f32 v20, v170, v171
	v_cvt_pk_bf16_f32 v21, v172, v173
	v_cvt_pk_bf16_f32 v22, v174, v175
	v_cvt_pk_bf16_f32 v23, v176, v177
	s_mov_b32 s17, 0x15000
	buffer_store_dwordx4 v[20:23], v150, s[4:7], s17 offen nt sc1
	v_pk_mul_f32 v[12:13], v[12:13], v[244:245] op_sel:[0,1] op_sel_hi:[1,1]
	v_pk_mul_f32 v[14:15], v[14:15], v[244:245] op_sel:[0,1] op_sel_hi:[1,1]
	v_pk_mul_f32 v[8:9], v[8:9], v[244:245] op_sel:[0,1] op_sel_hi:[1,1]
	v_pk_mul_f32 v[10:11], v[10:11], v[244:245] op_sel:[0,1] op_sel_hi:[1,1]
	v_max_f32_e32 v162, 0, v12
	v_max_f32_e32 v163, 0, v13
	v_max_f32_e32 v164, 0, v14
	v_max_f32_e32 v165, 0, v15
	v_max_f32_e32 v166, 0, v8
	v_max_f32_e32 v167, 0, v9
	v_max_f32_e32 v168, 0, v10
	v_max_f32_e32 v169, 0, v11
	v_pk_mul_f32 v[162:163], v[162:163], v[162:163]
	v_pk_mul_f32 v[164:165], v[164:165], v[164:165]
	v_pk_mul_f32 v[166:167], v[166:167], v[166:167]
	v_pk_mul_f32 v[168:169], v[168:169], v[168:169]
	v_cvt_pk_bf16_f32 v12, v162, v163
	v_cvt_pk_bf16_f32 v13, v164, v165
	v_cvt_pk_bf16_f32 v14, v166, v167
	v_cvt_pk_bf16_f32 v15, v168, v169
	s_mov_b32 s17, 0x5000
	buffer_store_dwordx4 v[12:15], v150, s[4:7], s17 offen offset:2048 nt sc1
	v_pk_mul_f32 v[4:5], v[4:5], v[244:245] op_sel:[0,1] op_sel_hi:[1,1]
	v_pk_mul_f32 v[6:7], v[6:7], v[244:245] op_sel:[0,1] op_sel_hi:[1,1]
	v_pk_mul_f32 v[0:1], v[0:1], v[244:245] op_sel:[0,1] op_sel_hi:[1,1]
	v_pk_mul_f32 v[2:3], v[2:3], v[244:245] op_sel:[0,1] op_sel_hi:[1,1]
	v_max_f32_e32 v170, 0, v4
	v_max_f32_e32 v171, 0, v5
	v_max_f32_e32 v172, 0, v6
	v_max_f32_e32 v173, 0, v7
	v_max_f32_e32 v174, 0, v0
	v_max_f32_e32 v175, 0, v1
	v_max_f32_e32 v176, 0, v2
	v_max_f32_e32 v177, 0, v3
	v_pk_mul_f32 v[170:171], v[170:171], v[170:171]
	v_pk_mul_f32 v[172:173], v[172:173], v[172:173]
	v_pk_mul_f32 v[174:175], v[174:175], v[174:175]
	v_pk_mul_f32 v[176:177], v[176:177], v[176:177]
	v_cvt_pk_bf16_f32 v4, v170, v171
	v_cvt_pk_bf16_f32 v5, v172, v173
	v_cvt_pk_bf16_f32 v6, v174, v175
	v_cvt_pk_bf16_f32 v7, v176, v177
	s_mov_b32 s17, 0x15000
	buffer_store_dwordx4 v[4:7], v150, s[4:7], s17 offen offset:2048 nt sc1
	s_andn2_b64 vcc, exec, s[0:1]
	s_mov_b64 s[0:1], -1
	s_cbranch_vccnz .LBB0_682
	s_andn2_b64 vcc, exec, s[10:11]
	s_cbranch_vccnz .LBB0_681
	s_barrier
	s_branch .LBB0_681
